# stack: barrier v2 + sc1 stores + group-local barriers (10 of 20) + relaxed GEMM transition waits
# baseline (speedup 1.0000x reference)
; __device__ __forceinline__ unsigned xb_ld(unsigned* p)              { return __hip_atomic_load(p, __ATOMIC_RELAXED, __HIP_MEMORY_SCOPE_AGENT); }
; __device__ __forceinline__ unsigned xb_add(unsigned* p, unsigned v) { return __hip_atomic_fetch_add(p, v, __ATOMIC_RELAXED, __HIP_MEMORY_SCOPE_AGENT); }
; #define XB_SPIN(cond, bar) do { unsigned _sp = 0; while (cond) { __builtin_amdgcn_s_sleep(1); \
;     if ((++_sp & 255u) == 0u) { if (xb_ld(&(bar)[XB_TMO])) break; if (_sp > XB_SPIN_CAP) { atomicAdd(&(bar)[XB_TMO], 1u); break; } } } } while (0)
; __device__ __forceinline__ void xcd_barrier(const XcdBarrier& b) {
;     asm volatile("s_waitcnt vmcnt(0)" ::: "memory");
;     __syncthreads();
;     if (threadIdx.x == 0) {
;         unsigned* bar = b.bar;
;         __builtin_amdgcn_s_waitcnt(0);
;         unsigned nloc = b.st[0], nx = b.st[1];
;         if (nloc == 0u) { xcd_barrier_complete(bar, b.x, nloc, nx); b.st[0] = nloc; b.st[1] = nx; }
;         const unsigned old = xb_add(&bar[XB_XSUB(b.x)], 1u);
;         const unsigned gen = old / nloc;
;         if (old + 1u == (gen + 1u) * nloc) {
;             __builtin_amdgcn_fence(__ATOMIC_RELEASE, "agent");
;             asm volatile("s_waitcnt vmcnt(0)" ::: "memory");
;             const unsigned og = xb_add(&bar[XB_TOP], 1u);
;             const unsigned tg = og / nx;
;             if (og + 1u == (tg + 1u) * nx) xb_add(&bar[XB_TOPGEN], 1u);
;             else XB_SPIN(xb_ld(&bar[XB_TOPGEN]) == tg, bar);
;             __builtin_amdgcn_fence(__ATOMIC_ACQUIRE, "agent");
;             xb_add(&bar[XB_XGEN(b.x)], 1u);
;             asm volatile("s_waitcnt vmcnt(0)" ::: "memory");
;         } else {
;             XB_SPIN(xb_ld(&bar[XB_XGEN(b.x)]) == gen, bar);
;             __builtin_amdgcn_fence(__ATOMIC_ACQUIRE, "agent");
;             asm volatile("s_waitcnt vmcnt(0)" ::: "memory");
;         }
;     }
;     __syncthreads();
; }
; __global__ void __launch_bounds__(NWAVES * 64, 2) trunk_fwd(Args args) {
;     ...
;         if (ph + 1 < args.ph_hi) xcd_barrier(bar);
.Lmy_lspin:
	global_load_dword v5, v99, s[2:3] sc1
	s_waitcnt vmcnt(0)
	v_readfirstlane_b32 s7, v5
	s_cmp_ge_u32 s7, s6
	s_cbranch_scc1 .Lmy_ldone
	s_sleep 1
	s_add_i32 s10, s10, 1
	s_cmp_lt_u32 s10, 0x10000
	s_cbranch_scc1 .Lmy_lspin

; __device__ __forceinline__ unsigned xb_ld(unsigned* p)              { return __hip_atomic_load(p, __ATOMIC_RELAXED, __HIP_MEMORY_SCOPE_AGENT); }
; __device__ __forceinline__ unsigned xb_add(unsigned* p, unsigned v) { return __hip_atomic_fetch_add(p, v, __ATOMIC_RELAXED, __HIP_MEMORY_SCOPE_AGENT); }
; #define XB_SPIN(cond, bar) do { unsigned _sp = 0; while (cond) { __builtin_amdgcn_s_sleep(1); \
;     if ((++_sp & 255u) == 0u) { if (xb_ld(&(bar)[XB_TMO])) break; if (_sp > XB_SPIN_CAP) { atomicAdd(&(bar)[XB_TMO], 1u); break; } } } } while (0)
; __device__ __forceinline__ void xcd_barrier(const XcdBarrier& b) {
;     asm volatile("s_waitcnt vmcnt(0)" ::: "memory");
;     __syncthreads();
;     if (threadIdx.x == 0) {
;         unsigned* bar = b.bar;
;         __builtin_amdgcn_s_waitcnt(0);
;         unsigned nloc = b.st[0], nx = b.st[1];
;         if (nloc == 0u) { xcd_barrier_complete(bar, b.x, nloc, nx); b.st[0] = nloc; b.st[1] = nx; }
;         const unsigned old = xb_add(&bar[XB_XSUB(b.x)], 1u);
;         const unsigned gen = old / nloc;
;         if (old + 1u == (gen + 1u) * nloc) {
;             __builtin_amdgcn_fence(__ATOMIC_RELEASE, "agent");
;             asm volatile("s_waitcnt vmcnt(0)" ::: "memory");
;             const unsigned og = xb_add(&bar[XB_TOP], 1u);
;             const unsigned tg = og / nx;
;             if (og + 1u == (tg + 1u) * nx) xb_add(&bar[XB_TOPGEN], 1u);
;             else XB_SPIN(xb_ld(&bar[XB_TOPGEN]) == tg, bar);
;             __builtin_amdgcn_fence(__ATOMIC_ACQUIRE, "agent");
;             xb_add(&bar[XB_XGEN(b.x)], 1u);
;             asm volatile("s_waitcnt vmcnt(0)" ::: "memory");
;         } else {
;             XB_SPIN(xb_ld(&bar[XB_XGEN(b.x)]) == gen, bar);
;             __builtin_amdgcn_fence(__ATOMIC_ACQUIRE, "agent");
;             asm volatile("s_waitcnt vmcnt(0)" ::: "memory");
;         }
;     }
;     __syncthreads();
; }
.Lmy_bar_spin:
	global_load_dword v5, v99, s[2:3] sc1
	s_waitcnt vmcnt(0)
	v_readfirstlane_b32 s11, v5
	s_cmp_ge_u32 s11, s7
	s_cbranch_scc1 .Lmy_bar_done
	s_sleep 1
	s_add_i32 s10, s10, 1
	s_cmp_lt_u32 s10, 0x10000
	s_cbranch_scc1 .Lmy_bar_spin
